# mask-free fast path for fully visible tiles in the NSA block-selection score loops (P14)
# baseline (speedup 1.0000x reference)
.LBB0_4226:
	v_readfirstlane_b32 s90, v47
	s_add_i32 s91, s48, 31
	s_nop 2
	s_cmp_le_u32 s91, s90
	s_cbranch_scc1 .Lp14a_fast
	ds_read_b128 v[2:5], v50
	ds_read_b128 v[54:57], v50 offset:32
	v_mov_b32_e32 v51, v0
	ds_read_b128 v[58:61], v50 offset:64
	ds_read_b128 v[62:65], v50 offset:96
	v_add_u32_e32 v53, s48, v48
	v_mov_b32_e32 v66, v52
	v_add_u32_e32 v52, 2, v53
	v_cmp_lt_u32_e32 vcc, v53, v47
	v_cmp_le_u32_e64 s[38:39], v53, v47
	s_waitcnt vmcnt(3) lgkmcnt(3)
	v_mfma_f32_32x32x16_bf16 v[0:15], v[2:5], v[16:19], 0
	v_cmp_le_u32_e64 s[6:7], v52, v47
	v_add_u32_e32 v67, 11, v53
	v_add_u32_e32 v68, 16, v53
	v_add_u32_e32 v69, 17, v53
	v_cmp_le_u32_e64 s[16:17], v67, v47
	v_cmp_le_u32_e64 s[18:19], v68, v47
	v_cmp_le_u32_e64 s[20:21], v69, v47
	s_waitcnt vmcnt(2) lgkmcnt(2)
	v_mfma_f32_32x32x16_bf16 v[0:15], v[54:57], v[20:23], v[0:15]
	v_add_u32_e32 v54, 3, v53
	v_add_u32_e32 v55, 8, v53
	v_add_u32_e32 v56, 9, v53
	v_cmp_le_u32_e64 s[8:9], v54, v47
	v_add_u32_e32 v57, 10, v53
	v_cmp_le_u32_e64 s[10:11], v55, v47
	v_cmp_le_u32_e64 s[12:13], v56, v47
	s_waitcnt vmcnt(1) lgkmcnt(1)
	v_mfma_f32_32x32x16_bf16 v[0:15], v[58:61], v[24:27], v[0:15]
	v_cmp_le_u32_e64 s[14:15], v57, v47
	v_add_u32_e32 v58, 18, v53
	v_add_u32_e32 v59, 19, v53
	v_add_u32_e32 v60, 24, v53
	v_add_u32_e32 v61, 25, v53
	v_cmp_le_u32_e64 s[24:25], v58, v47
	v_cmp_le_u32_e64 s[26:27], v59, v47
	s_waitcnt vmcnt(0) lgkmcnt(0)
	v_mfma_f32_32x32x16_bf16 v[0:15], v[62:65], v[28:31], v[0:15]
	v_add_u32_e32 v70, 26, v53
	v_add_u32_e32 v71, 27, v53
	v_cmp_le_u32_e64 s[28:29], v60, v47
	v_cmp_le_u32_e64 s[30:31], v61, v47
	v_cmp_le_u32_e64 s[34:35], v70, v47
	v_cmp_le_u32_e64 s[36:37], v71, v47
	s_add_i32 s48, s48, 32
	s_nop 4
	v_cndmask_b32_e64 v52, v42, v0, s[38:39]
	v_cndmask_b32_e32 v1, v42, v1, vcc
	v_cndmask_b32_e64 v2, v42, v2, s[6:7]
	v_cndmask_b32_e64 v3, v42, v3, s[8:9]
	v_max3_f32 v0, v51, v52, v1
	v_cndmask_b32_e64 v4, v42, v4, s[10:11]
	v_cndmask_b32_e64 v5, v42, v5, s[12:13]
	v_max3_f32 v0, v0, v2, v3
	v_cndmask_b32_e64 v6, v42, v6, s[14:15]
	v_cndmask_b32_e64 v7, v42, v7, s[16:17]
	v_max3_f32 v0, v0, v4, v5
	v_cndmask_b32_e64 v8, v42, v8, s[18:19]
	v_cndmask_b32_e64 v9, v42, v9, s[20:21]
	v_max3_f32 v0, v0, v6, v7
	v_cndmask_b32_e64 v10, v42, v10, s[24:25]
	v_cndmask_b32_e64 v11, v42, v11, s[26:27]
	v_max3_f32 v0, v0, v8, v9
	v_cndmask_b32_e64 v12, v42, v12, s[28:29]
	v_cndmask_b32_e64 v13, v42, v13, s[30:31]
	v_max3_f32 v0, v0, v10, v11
	v_cndmask_b32_e64 v14, v42, v14, s[34:35]
	v_cndmask_b32_e64 v15, v42, v15, s[36:37]
	v_max3_f32 v0, v0, v12, v13
	v_max3_f32 v0, v0, v14, v15
	v_sub_f32_e32 v52, v52, v0
	v_sub_f32_e32 v1, v1, v0
	v_exp_f32_e32 v52, v52
	v_sub_f32_e32 v2, v2, v0
	v_exp_f32_e32 v1, v1
	v_sub_f32_e32 v3, v3, v0
	v_exp_f32_e32 v2, v2
	v_sub_f32_e32 v4, v4, v0
	v_exp_f32_e32 v3, v3
	v_sub_f32_e32 v5, v5, v0
	v_exp_f32_e32 v4, v4
	v_add_f32_e32 v52, 0, v52
	v_sub_f32_e32 v6, v6, v0
	v_exp_f32_e32 v5, v5
	v_add_f32_e32 v1, v1, v52
	v_sub_f32_e32 v7, v7, v0
	v_exp_f32_e32 v6, v6
	v_add_f32_e32 v1, v2, v1
	v_sub_f32_e32 v8, v8, v0
	v_exp_f32_e32 v7, v7
	v_add_f32_e32 v1, v3, v1
	v_sub_f32_e32 v9, v9, v0
	v_exp_f32_e32 v8, v8
	v_add_f32_e32 v1, v4, v1
	v_sub_f32_e32 v10, v10, v0
	v_exp_f32_e32 v9, v9
	v_add_f32_e32 v1, v5, v1
	v_sub_f32_e32 v11, v11, v0
	v_exp_f32_e32 v10, v10
	v_add_f32_e32 v1, v6, v1
	v_sub_f32_e32 v12, v12, v0
	v_exp_f32_e32 v11, v11
	v_add_f32_e32 v1, v7, v1
	v_sub_f32_e32 v13, v13, v0
	v_exp_f32_e32 v12, v12
	v_add_f32_e32 v1, v8, v1
	v_sub_f32_e32 v14, v14, v0
	v_exp_f32_e32 v13, v13
	v_add_f32_e32 v1, v9, v1
	v_sub_f32_e32 v15, v15, v0
	v_exp_f32_e32 v14, v14
	v_add_f32_e32 v1, v10, v1
	v_sub_f32_e32 v51, v51, v0
	v_exp_f32_e32 v15, v15
	v_add_f32_e32 v1, v11, v1
	v_exp_f32_e32 v51, v51
	v_add_f32_e32 v1, v12, v1
	v_add_f32_e32 v1, v13, v1
	v_add_f32_e32 v1, v14, v1
	v_add_f32_e32 v52, v15, v1
	v_add_u32_e32 v50, 0x1200, v50
	s_cmp_lg_u32 s53, s48
	v_fmac_f32_e32 v52, v66, v51
	s_cbranch_scc1 .LBB0_4226
	s_branch .Lp14a_exit
.Lp14a_fast:
	ds_read_b128 v[2:5], v50
	ds_read_b128 v[54:57], v50 offset:32
	v_mov_b32_e32 v51, v0
	ds_read_b128 v[58:61], v50 offset:64
	ds_read_b128 v[62:65], v50 offset:96
	v_mov_b32_e32 v66, v52
	s_waitcnt vmcnt(3) lgkmcnt(3)
	v_mfma_f32_32x32x16_bf16 v[0:15], v[2:5], v[16:19], 0
	s_waitcnt vmcnt(2) lgkmcnt(2)
	v_mfma_f32_32x32x16_bf16 v[0:15], v[54:57], v[20:23], v[0:15]
	s_waitcnt vmcnt(1) lgkmcnt(1)
	v_mfma_f32_32x32x16_bf16 v[0:15], v[58:61], v[24:27], v[0:15]
	s_waitcnt vmcnt(0) lgkmcnt(0)
	v_mfma_f32_32x32x16_bf16 v[0:15], v[62:65], v[28:31], v[0:15]
	s_nop 7
	s_nop 4
	s_add_i32 s48, s48, 32
	s_nop 4
	v_mov_b32_e32 v52, v0
	v_max3_f32 v0, v51, v52, v1
	v_max3_f32 v0, v0, v2, v3
	v_max3_f32 v0, v0, v4, v5
	v_max3_f32 v0, v0, v6, v7
	v_max3_f32 v0, v0, v8, v9
	v_max3_f32 v0, v0, v10, v11
	v_max3_f32 v0, v0, v12, v13
	v_max3_f32 v0, v0, v14, v15
	v_sub_f32_e32 v52, v52, v0
	v_sub_f32_e32 v1, v1, v0
	v_exp_f32_e32 v52, v52
	v_sub_f32_e32 v2, v2, v0
	v_exp_f32_e32 v1, v1
	v_sub_f32_e32 v3, v3, v0
	v_exp_f32_e32 v2, v2
	v_sub_f32_e32 v4, v4, v0
	v_exp_f32_e32 v3, v3
	v_sub_f32_e32 v5, v5, v0
	v_exp_f32_e32 v4, v4
	v_add_f32_e32 v52, 0, v52
	v_sub_f32_e32 v6, v6, v0
	v_exp_f32_e32 v5, v5
	v_add_f32_e32 v1, v1, v52
	v_sub_f32_e32 v7, v7, v0
	v_exp_f32_e32 v6, v6
	v_add_f32_e32 v1, v2, v1
	v_sub_f32_e32 v8, v8, v0
	v_exp_f32_e32 v7, v7
	v_add_f32_e32 v1, v3, v1
	v_sub_f32_e32 v9, v9, v0
	v_exp_f32_e32 v8, v8
	v_add_f32_e32 v1, v4, v1
	v_sub_f32_e32 v10, v10, v0
	v_exp_f32_e32 v9, v9
	v_add_f32_e32 v1, v5, v1
	v_sub_f32_e32 v11, v11, v0
	v_exp_f32_e32 v10, v10
	v_add_f32_e32 v1, v6, v1
	v_sub_f32_e32 v12, v12, v0
	v_exp_f32_e32 v11, v11
	v_add_f32_e32 v1, v7, v1
	v_sub_f32_e32 v13, v13, v0
	v_exp_f32_e32 v12, v12
	v_add_f32_e32 v1, v8, v1
	v_sub_f32_e32 v14, v14, v0
	v_exp_f32_e32 v13, v13
	v_add_f32_e32 v1, v9, v1
	v_sub_f32_e32 v15, v15, v0
	v_exp_f32_e32 v14, v14
	v_add_f32_e32 v1, v10, v1
	v_sub_f32_e32 v51, v51, v0
	v_exp_f32_e32 v15, v15
	v_add_f32_e32 v1, v11, v1
	v_exp_f32_e32 v51, v51
	v_add_f32_e32 v1, v12, v1
	v_add_f32_e32 v1, v13, v1
	v_add_f32_e32 v1, v14, v1
	v_add_f32_e32 v52, v15, v1
	v_add_u32_e32 v50, 0x1200, v50
	s_cmp_lg_u32 s53, s48
	v_fmac_f32_e32 v52, v66, v51
	s_cbranch_scc1 .LBB0_4226
.Lp14a_exit:
	ds_bpermute_b32 v1, v40, v0
	v_max_f32_e32 v3, v0, v0
	ds_bpermute_b32 v2, v40, v52
	v_mov_b32_e32 v51, 0
	s_mov_b32 s30, 0
	s_waitcnt lgkmcnt(1)
	v_max_f32_e32 v4, v1, v1
	v_max_f32_e32 v50, v3, v4
	v_sub_f32_e32 v1, v1, v50
	v_sub_f32_e32 v0, v0, v50
	v_exp_f32_e32 v1, v1
	v_exp_f32_e32 v0, v0
	v_mov_b32_e32 v53, v32
	v_mov_b32_e32 v54, v46
	s_waitcnt lgkmcnt(0)
	v_mul_f32_e32 v1, v1, v2
	v_fmac_f32_e32 v1, v52, v0
	v_div_scale_f32 v0, s[6:7], v1, v1, 1.0
	v_rcp_f32_e32 v2, v0
	v_div_scale_f32 v3, vcc, 1.0, v1, 1.0
	v_fma_f32 v4, -v0, v2, 1.0
	v_fmac_f32_e32 v2, v4, v2
	v_mul_f32_e32 v4, v3, v2
	v_fma_f32 v5, -v0, v4, v3
	v_fmac_f32_e32 v4, v5, v2
	v_fma_f32 v0, -v0, v4, v3
	v_div_fmas_f32 v0, v0, v2, v4
	v_div_fixup_f32 v52, v0, v1, 1.0
.LBB0_4228:
	v_readfirstlane_b32 s90, v47
	s_add_i32 s91, s30, 31
	s_nop 2
	s_cmp_le_u32 s91, s90
	s_cbranch_scc1 .Lp14b_fast
	v_add_u32_e32 v0, 0x10000, v53
	v_add_u32_e32 v4, 0x10020, v53
	ds_read_b128 v[0:3], v0
	ds_read_b128 v[56:59], v4
	v_add_u32_e32 v55, 0x10040, v53
	v_add_u32_e32 v64, 0x10060, v53
	s_waitcnt lgkmcnt(1)
	v_mfma_f32_32x32x16_bf16 v[0:15], v[0:3], v[16:19], 0
	ds_read2st64_b32 v[68:69], v54 offset1:1
	ds_read2st64_b32 v[70:71], v54 offset0:2 offset1:3
	ds_read_b128 v[60:63], v55
	ds_read_b128 v[64:67], v64
	v_add_u32_e32 v72, s30, v48
	v_add_u32_e32 v55, 2, v72
	v_cmp_le_u32_e64 s[6:7], v55, v47
	v_add_u32_e32 v73, 11, v72
	v_cmp_lt_u32_e32 vcc, v72, v47
	s_waitcnt lgkmcnt(4)
	v_mfma_f32_32x32x16_bf16 v[0:15], v[56:59], v[20:23], v[0:15]
	v_add_u32_e32 v58, 9, v72
	v_add_u32_e32 v56, 3, v72
	v_add_u32_e32 v57, 8, v72
	v_cmp_le_u32_e64 s[10:11], v58, v47
	v_cmp_le_u32_e64 s[8:9], v57, v47
	v_cmp_le_u32_e64 s[28:29], v72, v47
	v_add_u32_e32 v74, 16, v72
	s_waitcnt lgkmcnt(1)
	v_mfma_f32_32x32x16_bf16 v[0:15], v[60:63], v[24:27], v[0:15]
	v_add_u32_e32 v61, 19, v72
	v_add_u32_e32 v75, 17, v72
	v_add_u32_e32 v60, 18, v72
	v_cmp_le_u32_e64 s[14:15], v74, v47
	v_cmp_le_u32_e64 s[16:17], v75, v47
	v_add_u32_e32 v59, 10, v72
	v_add_u32_e32 v77, 27, v72
	s_waitcnt lgkmcnt(0)
	v_mfma_f32_32x32x16_bf16 v[0:15], v[64:67], v[28:31], v[0:15]
	v_cmp_le_u32_e64 s[18:19], v60, v47
	v_cmp_le_u32_e64 s[12:13], v59, v47
	v_add_u32_e32 v62, 24, v72
	v_add_u32_e32 v63, 25, v72
	v_add_u32_e32 v76, 26, v72
	v_cmp_le_u32_e64 s[20:21], v62, v47
	v_cmp_le_u32_e64 s[24:25], v63, v47
	s_nop 4
	v_sub_f32_e32 v3, v3, v50
	v_sub_f32_e32 v5, v5, v50
	v_sub_f32_e32 v2, v2, v50
	v_sub_f32_e32 v4, v4, v50
	v_sub_f32_e32 v11, v11, v50
	v_exp_f32_e32 v3, v3
	v_exp_f32_e32 v5, v5
	v_sub_f32_e32 v0, v0, v50
	v_sub_f32_e32 v1, v1, v50
	v_sub_f32_e32 v7, v7, v50
	v_exp_f32_e32 v2, v2
	v_exp_f32_e32 v4, v4
	v_exp_f32_e32 v11, v11
	v_exp_f32_e32 v0, v0
	v_exp_f32_e32 v1, v1
	v_exp_f32_e32 v7, v7
	v_sub_f32_e32 v8, v8, v50
	v_sub_f32_e32 v9, v9, v50
	v_sub_f32_e32 v10, v10, v50
	v_sub_f32_e32 v15, v15, v50
	v_exp_f32_e32 v8, v8
	v_exp_f32_e32 v9, v9
	v_mul_f32_e32 v3, v52, v3
	v_mul_f32_e32 v5, v52, v5
	v_sub_f32_e32 v6, v6, v50
	v_exp_f32_e32 v10, v10
	v_exp_f32_e32 v15, v15
	v_mul_f32_e32 v2, v52, v2
	v_mul_f32_e32 v4, v52, v4
	v_mul_f32_e32 v11, v52, v11
	v_mul_f32_e32 v3, 0.5, v3
	v_cndmask_b32_e64 v5, 0, v5, s[10:11]
	v_cmp_le_u32_e64 s[10:11], v56, v47
	v_exp_f32_e32 v6, v6
	v_mul_f32_e32 v0, v52, v0
	v_mul_f32_e32 v1, v52, v1
	v_mul_f32_e32 v7, v52, v7
	v_cndmask_b32_e64 v2, 0, v2, s[6:7]
	v_cndmask_b32_e64 v4, 0, v4, s[8:9]
	v_mul_f32_e32 v11, 0.5, v11
	v_cmp_le_u32_e64 s[6:7], v61, v47
	v_cndmask_b32_e64 v3, 0, v3, s[10:11]
	v_cndmask_b32_e64 v0, 0, v0, s[28:29]
	v_cndmask_b32_e32 v1, 0, v1, vcc
	v_mul_f32_e32 v7, 0.5, v7
	v_cmp_le_u32_e32 vcc, v73, v47
	v_add_f32_e32 v4, v4, v5
	v_cndmask_b32_e64 v5, 0, v11, s[6:7]
	ds_bpermute_b32 v11, v40, v3
	v_sub_f32_e32 v12, v12, v50
	v_sub_f32_e32 v13, v13, v50
	v_mul_f32_e32 v8, v52, v8
	v_mul_f32_e32 v9, v52, v9
	v_add_f32_e32 v0, v0, v1
	v_cndmask_b32_e32 v1, 0, v7, vcc
	v_sub_f32_e32 v14, v14, v50
	v_exp_f32_e32 v12, v12
	v_exp_f32_e32 v13, v13
	v_mul_f32_e32 v10, v52, v10
	v_mul_f32_e32 v15, v52, v15
	v_cndmask_b32_e64 v8, 0, v8, s[14:15]
	v_cndmask_b32_e64 v9, 0, v9, s[16:17]
	v_add_f32_e32 v0, v2, v0
	ds_bpermute_b32 v2, v40, v1
	v_exp_f32_e32 v14, v14
	v_mul_f32_e32 v6, v52, v6
	v_cndmask_b32_e64 v10, 0, v10, s[18:19]
	v_mul_f32_e32 v15, 0.5, v15
	v_cmp_le_u32_e64 s[8:9], v77, v47
	v_add_f32_e32 v7, v8, v9
	v_cndmask_b32_e64 v6, 0, v6, s[12:13]
	v_cndmask_b32_e64 v8, 0, v15, s[8:9]
	v_add_f32_e32 v7, v10, v7
	v_add_f32_e32 v4, v6, v4
	ds_bpermute_b32 v6, v40, v5
	v_add_f32_e32 v0, v3, v0
	v_add_f32_e32 v3, v5, v7
	s_waitcnt lgkmcnt(2)
	v_cndmask_b32_e64 v5, v11, v51, s[4:5]
	ds_bpermute_b32 v51, v40, v8
	v_mul_f32_e32 v12, v52, v12
	v_mul_f32_e32 v13, v52, v13
	v_mul_f32_e32 v14, v52, v14
	v_cmp_le_u32_e64 s[26:27], v76, v47
	v_cndmask_b32_e64 v12, 0, v12, s[20:21]
	v_cndmask_b32_e64 v13, 0, v13, s[24:25]
	v_add_f32_e32 v1, v1, v4
	s_waitcnt lgkmcnt(2)
	v_cndmask_b32_e64 v7, v2, v11, s[4:5]
	v_cndmask_b32_e64 v14, 0, v14, s[26:27]
	v_add_f32_e32 v9, v12, v13
	v_add_f32_e32 v0, v5, v0
	v_add_f32_e32 v1, v7, v1
	v_add_f32_e32 v9, v14, v9
	v_add_f32_e32 v0, v68, v0
	v_add_f32_e32 v1, v69, v1
	v_add_f32_e32 v4, v8, v9
	s_waitcnt lgkmcnt(1)
	v_cndmask_b32_e64 v2, v6, v2, s[4:5]
	ds_write2st64_b32 v54, v0, v1 offset1:1
	s_waitcnt lgkmcnt(1)
	v_cndmask_b32_e64 v0, v51, v6, s[4:5]
	v_add_f32_e32 v2, v3, v2
	v_add_f32_e32 v0, v4, v0
	s_add_i32 s30, s30, 32
	v_add_f32_e32 v2, v70, v2
	v_add_f32_e32 v0, v71, v0
	v_add_u32_e32 v53, 0x1200, v53
	s_cmp_lg_u32 s53, s30
	ds_write2st64_b32 v54, v2, v0 offset0:2 offset1:3
	v_add_u32_e32 v54, 0x400, v54
	s_cbranch_scc1 .LBB0_4228
	s_branch .Lp14b_exit
.Lp14b_fast:
	v_add_u32_e32 v0, 0x10000, v53
	v_add_u32_e32 v4, 0x10020, v53
	ds_read_b128 v[0:3], v0
	ds_read_b128 v[56:59], v4
	v_add_u32_e32 v55, 0x10040, v53
	v_add_u32_e32 v64, 0x10060, v53
	s_waitcnt lgkmcnt(1)
	v_mfma_f32_32x32x16_bf16 v[0:15], v[0:3], v[16:19], 0
	ds_read2st64_b32 v[68:69], v54 offset1:1
	ds_read2st64_b32 v[70:71], v54 offset0:2 offset1:3
	ds_read_b128 v[60:63], v55
	ds_read_b128 v[64:67], v64
	s_waitcnt lgkmcnt(4)
	v_mfma_f32_32x32x16_bf16 v[0:15], v[56:59], v[20:23], v[0:15]
	s_waitcnt lgkmcnt(1)
	v_mfma_f32_32x32x16_bf16 v[0:15], v[60:63], v[24:27], v[0:15]
	s_waitcnt lgkmcnt(0)
	v_mfma_f32_32x32x16_bf16 v[0:15], v[64:67], v[28:31], v[0:15]
	s_nop 7
	s_nop 4
	s_nop 4
	v_sub_f32_e32 v3, v3, v50
	v_sub_f32_e32 v5, v5, v50
	v_sub_f32_e32 v2, v2, v50
	v_sub_f32_e32 v4, v4, v50
	v_sub_f32_e32 v11, v11, v50
	v_exp_f32_e32 v3, v3
	v_exp_f32_e32 v5, v5
	v_sub_f32_e32 v0, v0, v50
	v_sub_f32_e32 v1, v1, v50
	v_sub_f32_e32 v7, v7, v50
	v_exp_f32_e32 v2, v2
	v_exp_f32_e32 v4, v4
	v_exp_f32_e32 v11, v11
	v_exp_f32_e32 v0, v0
	v_exp_f32_e32 v1, v1
	v_exp_f32_e32 v7, v7
	v_sub_f32_e32 v8, v8, v50
	v_sub_f32_e32 v9, v9, v50
	v_sub_f32_e32 v10, v10, v50
	v_sub_f32_e32 v15, v15, v50
	v_exp_f32_e32 v8, v8
	v_exp_f32_e32 v9, v9
	v_mul_f32_e32 v3, v52, v3
	v_mul_f32_e32 v5, v52, v5
	v_sub_f32_e32 v6, v6, v50
	v_exp_f32_e32 v10, v10
	v_exp_f32_e32 v15, v15
	v_mul_f32_e32 v2, v52, v2
	v_mul_f32_e32 v4, v52, v4
	v_mul_f32_e32 v11, v52, v11
	v_mul_f32_e32 v3, 0.5, v3
	v_exp_f32_e32 v6, v6
	v_mul_f32_e32 v0, v52, v0
	v_mul_f32_e32 v1, v52, v1
	v_mul_f32_e32 v7, v52, v7
	v_mul_f32_e32 v11, 0.5, v11
	v_mul_f32_e32 v7, 0.5, v7
	v_add_f32_e32 v4, v4, v5
	v_mov_b32_e32 v5, v11
	ds_bpermute_b32 v11, v40, v3
	v_sub_f32_e32 v12, v12, v50
	v_sub_f32_e32 v13, v13, v50
	v_mul_f32_e32 v8, v52, v8
	v_mul_f32_e32 v9, v52, v9
	v_add_f32_e32 v0, v0, v1
	v_mov_b32_e32 v1, v7
	v_sub_f32_e32 v14, v14, v50
	v_exp_f32_e32 v12, v12
	v_exp_f32_e32 v13, v13
	v_mul_f32_e32 v10, v52, v10
	v_mul_f32_e32 v15, v52, v15
	v_add_f32_e32 v0, v2, v0
	ds_bpermute_b32 v2, v40, v1
	v_exp_f32_e32 v14, v14
	v_mul_f32_e32 v6, v52, v6
	v_mul_f32_e32 v15, 0.5, v15
	v_add_f32_e32 v7, v8, v9
	v_mov_b32_e32 v8, v15
	v_add_f32_e32 v7, v10, v7
	v_add_f32_e32 v4, v6, v4
	ds_bpermute_b32 v6, v40, v5
	v_add_f32_e32 v0, v3, v0
	v_add_f32_e32 v3, v5, v7
	s_waitcnt lgkmcnt(2)
	v_cndmask_b32_e64 v5, v11, v51, s[4:5]
	ds_bpermute_b32 v51, v40, v8
	v_mul_f32_e32 v12, v52, v12
	v_mul_f32_e32 v13, v52, v13
	v_mul_f32_e32 v14, v52, v14
	v_add_f32_e32 v1, v1, v4
	s_waitcnt lgkmcnt(2)
	v_cndmask_b32_e64 v7, v2, v11, s[4:5]
	v_add_f32_e32 v9, v12, v13
	v_add_f32_e32 v0, v5, v0
	v_add_f32_e32 v1, v7, v1
	v_add_f32_e32 v9, v14, v9
	v_add_f32_e32 v0, v68, v0
	v_add_f32_e32 v1, v69, v1
	v_add_f32_e32 v4, v8, v9
	s_waitcnt lgkmcnt(1)
	v_cndmask_b32_e64 v2, v6, v2, s[4:5]
	ds_write2st64_b32 v54, v0, v1 offset1:1
	s_waitcnt lgkmcnt(1)
	v_cndmask_b32_e64 v0, v51, v6, s[4:5]
	v_add_f32_e32 v2, v3, v2
	v_add_f32_e32 v0, v4, v0
	s_add_i32 s30, s30, 32
	v_add_f32_e32 v2, v70, v2
	v_add_f32_e32 v0, v71, v0
	v_add_u32_e32 v53, 0x1200, v53
	s_cmp_lg_u32 s53, s30
	ds_write2st64_b32 v54, v2, v0 offset0:2 offset1:3
	v_add_u32_e32 v54, 0x400, v54
	s_cbranch_scc1 .LBB0_4228
.Lp14b_exit:
	s_add_i32 s57, s57, 1
	s_cmp_eq_u32 s57, 4
	s_cbranch_scc0 .LBB0_4225
	s_add_i32 s12, s68, -1
	v_add_u32_e32 v0, -1, v45
	v_cmp_ne_u32_e64 s[6:7], s68, v45
	v_cmp_ne_u32_e64 s[8:9], s12, v45
	v_cmp_gt_u32_e32 vcc, s68, v0
	s_and_b64 s[6:7], s[6:7], s[8:9]
	s_and_b64 s[8:9], s[6:7], vcc
	v_mov_b32_e32 v0, 0xc0400000
	v_mov_b32_e32 v1, 0xc0400000
	s_and_saveexec_b64 s[6:7], s[8:9]
	ds_read_b32 v1, v46
	s_or_b64 exec, exec, s[6:7]
	v_or_b32_e32 v2, 2, v45
	v_add_u32_e32 v3, 1, v45
	v_cmp_ne_u32_e64 s[6:7], s68, v2
	v_cmp_ne_u32_e64 s[8:9], s12, v2
	v_cmp_gt_u32_e32 vcc, s68, v3
	s_and_b64 s[6:7], s[6:7], s[8:9]
	s_and_b64 s[8:9], s[6:7], vcc
	s_and_saveexec_b64 s[6:7], s[8:9]
	ds_read_b32 v0, v46 offset:256
	s_or_b64 exec, exec, s[6:7]
	v_or_b32_e32 v2, 4, v45
	v_add_u32_e32 v3, 3, v45
	v_cmp_ne_u32_e64 s[6:7], s68, v2
	v_cmp_ne_u32_e64 s[8:9], s12, v2
	v_cmp_gt_u32_e32 vcc, s68, v3
	s_and_b64 s[6:7], s[6:7], s[8:9]
	s_and_b64 s[8:9], s[6:7], vcc
	v_mov_b32_e32 v2, 0xc0400000
	v_mov_b32_e32 v3, 0xc0400000
	s_and_saveexec_b64 s[6:7], s[8:9]
	ds_read_b32 v3, v46 offset:512
	s_or_b64 exec, exec, s[6:7]
	v_or_b32_e32 v4, 6, v45
	v_add_u32_e32 v5, 5, v45
	v_cmp_ne_u32_e64 s[6:7], s68, v4
	v_cmp_ne_u32_e64 s[8:9], s12, v4
	v_cmp_gt_u32_e32 vcc, s68, v5
	s_and_b64 s[6:7], s[6:7], s[8:9]
	s_and_b64 s[8:9], s[6:7], vcc
	s_and_saveexec_b64 s[6:7], s[8:9]
	ds_read_b32 v2, v46 offset:768
	s_or_b64 exec, exec, s[6:7]
	v_or_b32_e32 v4, 8, v45
	v_add_u32_e32 v5, 7, v45
	v_cmp_ne_u32_e64 s[6:7], s68, v4
	v_cmp_ne_u32_e64 s[8:9], s12, v4
	v_cmp_gt_u32_e32 vcc, s68, v5
	s_and_b64 s[6:7], s[6:7], s[8:9]
	s_and_b64 s[8:9], s[6:7], vcc
	v_mov_b32_e32 v4, 0xc0400000
	v_mov_b32_e32 v5, 0xc0400000
	s_and_saveexec_b64 s[6:7], s[8:9]
	ds_read_b32 v5, v46 offset:1024
	s_or_b64 exec, exec, s[6:7]
	v_or_b32_e32 v6, 10, v45
	v_add_u32_e32 v7, 9, v45
	v_cmp_ne_u32_e64 s[6:7], s68, v6
	v_cmp_ne_u32_e64 s[8:9], s12, v6
	v_cmp_gt_u32_e32 vcc, s68, v7
	s_and_b64 s[6:7], s[6:7], s[8:9]
	s_and_b64 s[8:9], s[6:7], vcc
	s_and_saveexec_b64 s[6:7], s[8:9]
	ds_read_b32 v4, v46 offset:1280
	s_or_b64 exec, exec, s[6:7]
	v_or_b32_e32 v6, 12, v45
	v_add_u32_e32 v7, 11, v45
	v_cmp_ne_u32_e64 s[6:7], s68, v6
	v_cmp_ne_u32_e64 s[8:9], s12, v6
	v_cmp_gt_u32_e32 vcc, s68, v7
	s_and_b64 s[6:7], s[6:7], s[8:9]
	s_and_b64 s[8:9], s[6:7], vcc
	v_mov_b32_e32 v6, 0xc0400000
	v_mov_b32_e32 v7, 0xc0400000
	s_and_saveexec_b64 s[6:7], s[8:9]
	ds_read_b32 v7, v46 offset:1536
	s_or_b64 exec, exec, s[6:7]
	v_or_b32_e32 v8, 14, v45
	v_add_u32_e32 v9, 13, v45
	v_cmp_ne_u32_e64 s[6:7], s68, v8
	v_cmp_ne_u32_e64 s[8:9], s12, v8
	v_cmp_gt_u32_e32 vcc, s68, v9
	s_and_b64 s[6:7], s[6:7], s[8:9]
	s_and_b64 s[8:9], s[6:7], vcc
	s_and_saveexec_b64 s[6:7], s[8:9]
	ds_read_b32 v6, v46 offset:1792
	s_or_b64 exec, exec, s[6:7]
	v_or_b32_e32 v8, 16, v45
	v_add_u32_e32 v9, 15, v45
	v_cmp_ne_u32_e64 s[6:7], s68, v8
	v_cmp_ne_u32_e64 s[8:9], s12, v8
	v_cmp_gt_u32_e32 vcc, s68, v9
	s_and_b64 s[6:7], s[6:7], s[8:9]
	s_and_b64 s[8:9], s[6:7], vcc
	v_mov_b32_e32 v8, 0xc0400000
	v_mov_b32_e32 v9, 0xc0400000
	s_and_saveexec_b64 s[6:7], s[8:9]
	ds_read_b32 v9, v46 offset:2048
	s_or_b64 exec, exec, s[6:7]
	v_or_b32_e32 v10, 18, v45
	v_add_u32_e32 v11, 17, v45
	v_cmp_ne_u32_e64 s[6:7], s68, v10
	v_cmp_ne_u32_e64 s[8:9], s12, v10
	v_cmp_gt_u32_e32 vcc, s68, v11
	s_and_b64 s[6:7], s[6:7], s[8:9]
	s_and_b64 s[8:9], s[6:7], vcc
	s_and_saveexec_b64 s[6:7], s[8:9]
	ds_read_b32 v8, v46 offset:2304
	s_or_b64 exec, exec, s[6:7]
	v_or_b32_e32 v10, 20, v45
	v_add_u32_e32 v11, 19, v45
	v_cmp_ne_u32_e64 s[6:7], s68, v10
	v_cmp_ne_u32_e64 s[8:9], s12, v10
	v_cmp_gt_u32_e32 vcc, s68, v11
	s_and_b64 s[6:7], s[6:7], s[8:9]
	s_and_b64 s[8:9], s[6:7], vcc
	v_mov_b32_e32 v10, 0xc0400000
	v_mov_b32_e32 v11, 0xc0400000
	s_and_saveexec_b64 s[6:7], s[8:9]
	ds_read_b32 v11, v46 offset:2560
	s_or_b64 exec, exec, s[6:7]
	v_or_b32_e32 v12, 22, v45
	v_add_u32_e32 v13, 21, v45
	v_cmp_ne_u32_e64 s[6:7], s68, v12
	v_cmp_ne_u32_e64 s[8:9], s12, v12
	v_cmp_gt_u32_e32 vcc, s68, v13
	s_and_b64 s[6:7], s[6:7], s[8:9]
	s_and_b64 s[8:9], s[6:7], vcc
	s_and_saveexec_b64 s[6:7], s[8:9]
	ds_read_b32 v10, v46 offset:2816
	s_or_b64 exec, exec, s[6:7]
	v_or_b32_e32 v12, 24, v45
	v_add_u32_e32 v13, 23, v45
	v_cmp_ne_u32_e64 s[6:7], s68, v12
	v_cmp_ne_u32_e64 s[8:9], s12, v12
	v_cmp_gt_u32_e32 vcc, s68, v13
	s_and_b64 s[6:7], s[6:7], s[8:9]
	s_and_b64 s[8:9], s[6:7], vcc
	v_mov_b32_e32 v12, 0xc0400000
	v_mov_b32_e32 v13, 0xc0400000
	s_and_saveexec_b64 s[6:7], s[8:9]
	ds_read_b32 v13, v46 offset:3072
	s_or_b64 exec, exec, s[6:7]
	v_or_b32_e32 v14, 26, v45
	v_add_u32_e32 v15, 25, v45
	v_cmp_ne_u32_e64 s[6:7], s68, v14
	v_cmp_ne_u32_e64 s[8:9], s12, v14
	v_cmp_gt_u32_e32 vcc, s68, v15
	s_and_b64 s[6:7], s[6:7], s[8:9]
	s_and_b64 s[8:9], s[6:7], vcc
	s_and_saveexec_b64 s[6:7], s[8:9]
	ds_read_b32 v12, v46 offset:3328
	s_or_b64 exec, exec, s[6:7]
	v_or_b32_e32 v14, 28, v45
	v_add_u32_e32 v15, 27, v45
	v_cmp_ne_u32_e64 s[6:7], s68, v14
	v_cmp_ne_u32_e64 s[8:9], s12, v14
	v_cmp_gt_u32_e32 vcc, s68, v15
	s_and_b64 s[6:7], s[6:7], s[8:9]
	s_and_b64 s[8:9], s[6:7], vcc
	v_mov_b32_e32 v14, 0xc0400000
	v_mov_b32_e32 v15, 0xc0400000
	s_and_saveexec_b64 s[6:7], s[8:9]
	ds_read_b32 v15, v46 offset:3584
	s_or_b64 exec, exec, s[6:7]
	v_or_b32_e32 v16, 30, v45
	v_add_u32_e32 v17, 29, v45
	v_cmp_ne_u32_e64 s[6:7], s68, v16
	v_cmp_ne_u32_e64 s[8:9], s12, v16
	v_cmp_gt_u32_e32 vcc, s68, v17
	s_and_b64 s[6:7], s[6:7], s[8:9]
	s_and_b64 s[8:9], s[6:7], vcc
	s_and_saveexec_b64 s[6:7], s[8:9]
	ds_read_b32 v14, v46 offset:3840
	s_or_b64 exec, exec, s[6:7]
	v_or_b32_e32 v16, 32, v45
	v_add_u32_e32 v17, 31, v45
	v_cmp_ne_u32_e64 s[6:7], s68, v16
	v_cmp_ne_u32_e64 s[8:9], s12, v16
	v_cmp_gt_u32_e32 vcc, s68, v17
	s_and_b64 s[6:7], s[6:7], s[8:9]
	s_and_b64 s[8:9], s[6:7], vcc
	v_mov_b32_e32 v16, 0xc0400000
	v_mov_b32_e32 v17, 0xc0400000
	s_and_saveexec_b64 s[6:7], s[8:9]
	ds_read_b32 v17, v46 offset:4096
	s_or_b64 exec, exec, s[6:7]
	v_or_b32_e32 v18, 34, v45
	v_add_u32_e32 v19, 33, v45
	v_cmp_ne_u32_e64 s[6:7], s68, v18
	v_cmp_ne_u32_e64 s[8:9], s12, v18
	v_cmp_gt_u32_e32 vcc, s68, v19
	s_and_b64 s[6:7], s[6:7], s[8:9]
	s_and_b64 s[8:9], s[6:7], vcc
	s_and_saveexec_b64 s[6:7], s[8:9]
	ds_read_b32 v16, v46 offset:4352
	s_or_b64 exec, exec, s[6:7]
	v_or_b32_e32 v18, 36, v45
	v_add_u32_e32 v19, 35, v45
	v_cmp_ne_u32_e64 s[6:7], s68, v18
	v_cmp_ne_u32_e64 s[8:9], s12, v18
	v_cmp_gt_u32_e32 vcc, s68, v19
	s_and_b64 s[6:7], s[6:7], s[8:9]
	s_and_b64 s[8:9], s[6:7], vcc
	v_mov_b32_e32 v18, 0xc0400000
	v_mov_b32_e32 v19, 0xc0400000
	s_and_saveexec_b64 s[6:7], s[8:9]
	ds_read_b32 v19, v46 offset:4608
	s_or_b64 exec, exec, s[6:7]
	v_or_b32_e32 v20, 38, v45
	v_add_u32_e32 v21, 37, v45
	v_cmp_ne_u32_e64 s[6:7], s68, v20
	v_cmp_ne_u32_e64 s[8:9], s12, v20
	v_cmp_gt_u32_e32 vcc, s68, v21
	s_and_b64 s[6:7], s[6:7], s[8:9]
	s_and_b64 s[8:9], s[6:7], vcc
	s_and_saveexec_b64 s[6:7], s[8:9]
	ds_read_b32 v18, v46 offset:4864
	s_or_b64 exec, exec, s[6:7]
	v_or_b32_e32 v20, 40, v45
	v_add_u32_e32 v21, 39, v45
	v_cmp_ne_u32_e64 s[6:7], s68, v20
	v_cmp_ne_u32_e64 s[8:9], s12, v20
	v_cmp_gt_u32_e32 vcc, s68, v21
	s_and_b64 s[6:7], s[6:7], s[8:9]
	s_and_b64 s[8:9], s[6:7], vcc
	v_mov_b32_e32 v20, 0xc0400000
	v_mov_b32_e32 v21, 0xc0400000
	s_and_saveexec_b64 s[6:7], s[8:9]
	ds_read_b32 v21, v46 offset:5120
	s_or_b64 exec, exec, s[6:7]
	v_or_b32_e32 v22, 42, v45
	v_add_u32_e32 v23, 41, v45
	v_cmp_ne_u32_e64 s[6:7], s68, v22
	v_cmp_ne_u32_e64 s[8:9], s12, v22
	v_cmp_gt_u32_e32 vcc, s68, v23
	s_and_b64 s[6:7], s[6:7], s[8:9]
	s_and_b64 s[8:9], s[6:7], vcc
	s_and_saveexec_b64 s[6:7], s[8:9]
	ds_read_b32 v20, v46 offset:5376
	s_or_b64 exec, exec, s[6:7]
	v_or_b32_e32 v22, 44, v45
	v_add_u32_e32 v23, 43, v45
	v_cmp_ne_u32_e64 s[6:7], s68, v22
	v_cmp_ne_u32_e64 s[8:9], s12, v22
	v_cmp_gt_u32_e32 vcc, s68, v23
	s_and_b64 s[6:7], s[6:7], s[8:9]
	s_and_b64 s[8:9], s[6:7], vcc
	v_mov_b32_e32 v22, 0xc0400000
	v_mov_b32_e32 v23, 0xc0400000
	s_and_saveexec_b64 s[6:7], s[8:9]
	ds_read_b32 v23, v46 offset:5632
	s_or_b64 exec, exec, s[6:7]
	v_or_b32_e32 v24, 46, v45
	v_add_u32_e32 v25, 45, v45
	v_cmp_ne_u32_e64 s[6:7], s68, v24
	v_cmp_ne_u32_e64 s[8:9], s12, v24
	v_cmp_gt_u32_e32 vcc, s68, v25
	s_and_b64 s[6:7], s[6:7], s[8:9]
	s_and_b64 s[8:9], s[6:7], vcc
	s_and_saveexec_b64 s[6:7], s[8:9]
	ds_read_b32 v22, v46 offset:5888
	s_or_b64 exec, exec, s[6:7]
	v_or_b32_e32 v24, 48, v45
	v_add_u32_e32 v25, 47, v45
	v_cmp_ne_u32_e64 s[6:7], s68, v24
	v_cmp_ne_u32_e64 s[8:9], s12, v24
	v_cmp_gt_u32_e32 vcc, s68, v25
	s_and_b64 s[6:7], s[6:7], s[8:9]
	s_and_b64 s[8:9], s[6:7], vcc
	v_mov_b32_e32 v24, 0xc0400000
	v_mov_b32_e32 v25, 0xc0400000
	s_and_saveexec_b64 s[6:7], s[8:9]
	ds_read_b32 v25, v46 offset:6144
	s_or_b64 exec, exec, s[6:7]
	v_or_b32_e32 v26, 50, v45
	v_add_u32_e32 v27, 49, v45
	v_cmp_ne_u32_e64 s[6:7], s68, v26
	v_cmp_ne_u32_e64 s[8:9], s12, v26
	v_cmp_gt_u32_e32 vcc, s68, v27
	s_and_b64 s[6:7], s[6:7], s[8:9]
	s_and_b64 s[8:9], s[6:7], vcc
	s_and_saveexec_b64 s[6:7], s[8:9]
	ds_read_b32 v24, v46 offset:6400
	s_or_b64 exec, exec, s[6:7]
	v_or_b32_e32 v26, 52, v45
	v_add_u32_e32 v27, 51, v45
	v_cmp_ne_u32_e64 s[6:7], s68, v26
	v_cmp_ne_u32_e64 s[8:9], s12, v26
	v_cmp_gt_u32_e32 vcc, s68, v27
	s_and_b64 s[6:7], s[6:7], s[8:9]
	s_and_b64 s[8:9], s[6:7], vcc
	v_mov_b32_e32 v26, 0xc0400000
	v_mov_b32_e32 v27, 0xc0400000
	s_and_saveexec_b64 s[6:7], s[8:9]
	ds_read_b32 v27, v46 offset:6656
	s_or_b64 exec, exec, s[6:7]
	v_or_b32_e32 v28, 54, v45
	v_add_u32_e32 v29, 53, v45
	v_cmp_ne_u32_e64 s[6:7], s68, v28
	v_cmp_ne_u32_e64 s[8:9], s12, v28
	v_cmp_gt_u32_e32 vcc, s68, v29
	s_and_b64 s[6:7], s[6:7], s[8:9]
	s_and_b64 s[8:9], s[6:7], vcc
	s_and_saveexec_b64 s[6:7], s[8:9]
	ds_read_b32 v26, v46 offset:6912
	s_or_b64 exec, exec, s[6:7]
	v_or_b32_e32 v28, 56, v45
	v_add_u32_e32 v29, 55, v45
	v_cmp_ne_u32_e64 s[6:7], s68, v28
	v_cmp_ne_u32_e64 s[8:9], s12, v28
	v_cmp_gt_u32_e32 vcc, s68, v29
	s_and_b64 s[6:7], s[6:7], s[8:9]
	s_and_b64 s[8:9], s[6:7], vcc
	v_mov_b32_e32 v28, 0xc0400000
	v_mov_b32_e32 v29, 0xc0400000
	s_and_saveexec_b64 s[6:7], s[8:9]
	ds_read_b32 v29, v46 offset:7168
	s_or_b64 exec, exec, s[6:7]
	v_or_b32_e32 v30, 58, v45
	v_add_u32_e32 v31, 57, v45
	v_cmp_ne_u32_e64 s[6:7], s68, v30
	v_cmp_ne_u32_e64 s[8:9], s12, v30
	v_cmp_gt_u32_e32 vcc, s68, v31
	s_and_b64 s[6:7], s[6:7], s[8:9]
	s_and_b64 s[8:9], s[6:7], vcc
	s_and_saveexec_b64 s[6:7], s[8:9]
	ds_read_b32 v28, v46 offset:7424
	s_or_b64 exec, exec, s[6:7]
	v_or_b32_e32 v30, 60, v45
	v_add_u32_e32 v31, 59, v45
	v_cmp_ne_u32_e64 s[6:7], s68, v30
	v_cmp_ne_u32_e64 s[8:9], s12, v30
	v_cmp_gt_u32_e32 vcc, s68, v31
	s_and_b64 s[6:7], s[6:7], s[8:9]
	s_and_b64 s[8:9], s[6:7], vcc
	v_mov_b32_e32 v30, 0xc0400000
	v_mov_b32_e32 v31, 0xc0400000
	s_and_saveexec_b64 s[6:7], s[8:9]
	ds_read_b32 v31, v46 offset:7680
	s_or_b64 exec, exec, s[6:7]
	v_or_b32_e32 v32, 62, v45
	v_add_u32_e32 v36, 61, v45
	v_cmp_ne_u32_e64 s[6:7], s68, v32
	v_cmp_ne_u32_e64 s[8:9], s12, v32
	v_cmp_gt_u32_e32 vcc, s68, v36
	s_and_b64 s[6:7], s[6:7], s[8:9]
	s_and_b64 s[8:9], s[6:7], vcc
	s_and_saveexec_b64 s[6:7], s[8:9]
	ds_read_b32 v30, v46 offset:7936
	s_or_b64 exec, exec, s[6:7]
	v_mov_b32_e32 v32, 0
	s_mov_b32 s13, 13
	s_branch .LBB0_4296
